# UP epilogue: leading half takes its alignment barrier after its own affine/exchange-write part (overlaps the trailing half's last MFMA block)
# baseline (speedup 1.0000x reference)
.LBB0_557:
	ds_read_b128 v[30:33], v219
	ds_read_b128 v[54:57], v219 offset:1024
	ds_read_b128 v[118:121], v219 offset:2048
	ds_read_b128 v[122:125], v219 offset:3072
	ds_read_b128 v[146:149], v220
	ds_read_b128 v[150:153], v220 offset:1024
	ds_read_b128 v[154:157], v220 offset:2048
	ds_read_b128 v[158:161], v220 offset:3072
	s_add_u32 s48, s8, 0xfffc0080
	s_addc_u32 s49, s9, -1
	s_cmp_eq_u32 s7, 12
	s_cselect_b32 s51, s41, s49
	s_cselect_b32 s50, s47, s48
	s_cselect_b32 s49, s39, s3
	s_cselect_b32 s48, vcc_lo, vcc_hi
	s_add_i32 m0, s70, 0xc000
	ds_read_b128 v[162:165], v221
	ds_read_b128 v[166:169], v221 offset:1024
	ds_read_b128 v[194:197], v221 offset:2048
	ds_read_b128 v[198:201], v221 offset:3072
	ds_read_b128 v[202:205], v221 offset:4096
	ds_read_b128 v[206:209], v221 offset:5120
	ds_read_b128 v[224:227], v221 offset:6144
	ds_read_b128 v[228:231], v221 offset:7168
	global_load_lds_dwordx4 v186, s[8:9]
	s_add_i32 m0, s70, 0xe000
	s_nop 0
	global_load_lds_dwordx4 v188, s[8:9]
	s_waitcnt vmcnt(8)
	s_waitcnt lgkmcnt(0)
	s_barrier
	s_setprio 1
	v_mfma_f32_16x16x32_bf16 v[62:65], v[30:33], v[162:165], v[62:65]
	v_mfma_f32_16x16x32_bf16 v[42:45], v[118:121], v[162:165], v[42:45]
	v_mfma_f32_16x16x32_bf16 v[50:53], v[30:33], v[194:197], v[50:53]
	v_mfma_f32_16x16x32_bf16 v[38:41], v[118:121], v[194:197], v[38:41]
	v_mfma_f32_16x16x32_bf16 v[46:49], v[30:33], v[202:205], v[46:49]
	v_mfma_f32_16x16x32_bf16 v[34:37], v[118:121], v[202:205], v[34:37]
	v_mfma_f32_16x16x32_bf16 v[142:145], v[30:33], v[224:227], v[142:145]
	v_mfma_f32_16x16x32_bf16 v[82:85], v[118:121], v[224:227], v[82:85]
	v_mfma_f32_16x16x32_bf16 v[62:65], v[54:57], v[166:169], v[62:65]
	v_mfma_f32_16x16x32_bf16 v[42:45], v[122:125], v[166:169], v[42:45]
	v_mfma_f32_16x16x32_bf16 v[50:53], v[54:57], v[198:201], v[50:53]
	v_mfma_f32_16x16x32_bf16 v[38:41], v[122:125], v[198:201], v[38:41]
	v_mfma_f32_16x16x32_bf16 v[46:49], v[54:57], v[206:209], v[46:49]
	v_mfma_f32_16x16x32_bf16 v[34:37], v[122:125], v[206:209], v[34:37]
	v_mfma_f32_16x16x32_bf16 v[142:145], v[54:57], v[228:231], v[142:145]
	v_mfma_f32_16x16x32_bf16 v[82:85], v[122:125], v[228:231], v[82:85]
	v_mfma_f32_16x16x32_bf16 v[134:137], v[146:149], v[162:165], v[134:137]
	v_mfma_f32_16x16x32_bf16 v[74:77], v[154:157], v[162:165], v[74:77]
	v_mfma_f32_16x16x32_bf16 v[130:133], v[146:149], v[194:197], v[130:133]
	v_mfma_f32_16x16x32_bf16 v[70:73], v[154:157], v[194:197], v[70:73]
	v_mfma_f32_16x16x32_bf16 v[78:81], v[146:149], v[202:205], v[78:81]
	v_mfma_f32_16x16x32_bf16 v[66:69], v[154:157], v[202:205], v[66:69]
	v_mfma_f32_16x16x32_bf16 v[138:141], v[146:149], v[224:227], v[138:141]
	v_mfma_f32_16x16x32_bf16 v[98:101], v[154:157], v[224:227], v[98:101]
	v_mfma_f32_16x16x32_bf16 v[134:137], v[150:153], v[166:169], v[134:137]
	v_mfma_f32_16x16x32_bf16 v[74:77], v[158:161], v[166:169], v[74:77]
	v_mfma_f32_16x16x32_bf16 v[130:133], v[150:153], v[198:201], v[130:133]
	v_mfma_f32_16x16x32_bf16 v[70:73], v[158:161], v[198:201], v[70:73]
	v_mfma_f32_16x16x32_bf16 v[78:81], v[150:153], v[206:209], v[78:81]
	v_mfma_f32_16x16x32_bf16 v[66:69], v[158:161], v[206:209], v[66:69]
	v_mfma_f32_16x16x32_bf16 v[138:141], v[150:153], v[228:231], v[138:141]
	v_mfma_f32_16x16x32_bf16 v[98:101], v[158:161], v[228:231], v[98:101]
	s_setprio 0
	s_barrier
	s_add_u32 s98, s48, 0x80
	s_addc_u32 s99, s49, 0
	s_add_u32 s100, s50, 0x80
	s_addc_u32 s101, s51, 0
	s_add_i32 s84, s93, s64
	s_mov_b32 m0, s84
	ds_read_b128 v[162:165], v221 offset:16384
	ds_read_b128 v[166:169], v221 offset:17408
	ds_read_b128 v[194:197], v221 offset:18432
	ds_read_b128 v[198:201], v221 offset:19456
	ds_read_b128 v[202:205], v221 offset:20480
	ds_read_b128 v[206:209], v221 offset:21504
	ds_read_b128 v[224:227], v221 offset:22528
	ds_read_b128 v[228:231], v221 offset:23552
	global_load_lds_dwordx4 v176, s[48:49]
	s_add_i32 m0, s84, 0x2000
	s_add_u32 s84, s48, 0x40000
	s_addc_u32 s85, s49, 0
	s_add_i32 s86, s90, s64
	global_load_lds_dwordx4 v180, s[48:49]
	s_mov_b32 m0, s86
	s_nop 0
	global_load_lds_dwordx4 v176, s[84:85]
	s_add_i32 m0, s86, 0x2000
	s_nop 0
	global_load_lds_dwordx4 v180, s[84:85]
	s_mov_b32 m0, s70
	s_nop 0
	global_load_lds_dwordx4 v174, s[50:51]
	s_mov_b32 m0, s71
	s_nop 0
	global_load_lds_dwordx4 v178, s[50:51]
	s_waitcnt vmcnt(8)
	s_waitcnt lgkmcnt(0)
	s_barrier
	s_setprio 1
	v_mfma_f32_16x16x32_bf16 v[94:97], v[30:33], v[162:165], v[94:97]
	v_mfma_f32_16x16x32_bf16 v[10:13], v[118:121], v[162:165], v[10:13]
	v_mfma_f32_16x16x32_bf16 v[90:93], v[30:33], v[194:197], v[90:93]
	v_mfma_f32_16x16x32_bf16 v[6:9], v[118:121], v[194:197], v[6:9]
	v_mfma_f32_16x16x32_bf16 v[86:89], v[30:33], v[202:205], v[86:89]
	v_mfma_f32_16x16x32_bf16 v[2:5], v[118:121], v[202:205], v[2:5]
	v_mfma_f32_16x16x32_bf16 v[26:29], v[118:121], v[224:227], v[26:29]
	v_mfma_f32_16x16x32_bf16 v[94:97], v[54:57], v[166:169], v[94:97]
	v_mfma_f32_16x16x32_bf16 v[10:13], v[122:125], v[166:169], v[10:13]
	v_mfma_f32_16x16x32_bf16 v[90:93], v[54:57], v[198:201], v[90:93]
	v_mfma_f32_16x16x32_bf16 v[6:9], v[122:125], v[198:201], v[6:9]
	v_mfma_f32_16x16x32_bf16 v[86:89], v[54:57], v[206:209], v[86:89]
	v_mfma_f32_16x16x32_bf16 v[2:5], v[122:125], v[206:209], v[2:5]
	v_mfma_f32_16x16x32_bf16 v[30:33], v[30:33], v[224:227], v[114:117]
	v_mfma_f32_16x16x32_bf16 v[26:29], v[122:125], v[228:231], v[26:29]
	v_mfma_f32_16x16x32_bf16 v[30:33], v[54:57], v[228:231], v[30:33]
	v_mfma_f32_16x16x32_bf16 v[22:25], v[154:157], v[162:165], v[22:25]
	v_mfma_f32_16x16x32_bf16 v[106:109], v[146:149], v[194:197], v[106:109]
	v_mfma_f32_16x16x32_bf16 v[18:21], v[154:157], v[194:197], v[18:21]
	v_mfma_f32_16x16x32_bf16 v[102:105], v[146:149], v[202:205], v[102:105]
	v_mfma_f32_16x16x32_bf16 v[14:17], v[154:157], v[202:205], v[14:17]
	v_mfma_f32_16x16x32_bf16 v[58:61], v[154:157], v[224:227], v[58:61]
	v_mfma_f32_16x16x32_bf16 v[54:57], v[146:149], v[162:165], v[110:113]
	v_mfma_f32_16x16x32_bf16 v[22:25], v[158:161], v[166:169], v[22:25]
	v_mfma_f32_16x16x32_bf16 v[106:109], v[150:153], v[198:201], v[106:109]
	v_mfma_f32_16x16x32_bf16 v[18:21], v[158:161], v[198:201], v[18:21]
	v_mfma_f32_16x16x32_bf16 v[102:105], v[150:153], v[206:209], v[102:105]
	v_mfma_f32_16x16x32_bf16 v[14:17], v[158:161], v[206:209], v[14:17]
	v_mfma_f32_16x16x32_bf16 v[110:113], v[146:149], v[224:227], v[126:129]
	v_mfma_f32_16x16x32_bf16 v[58:61], v[158:161], v[228:231], v[58:61]
	v_mfma_f32_16x16x32_bf16 v[54:57], v[150:153], v[166:169], v[54:57]
	v_mfma_f32_16x16x32_bf16 v[118:121], v[150:153], v[228:231], v[110:113]
	s_setprio 0
	s_barrier
	s_add_i32 s84, 0, 0x18000
	v_add_u32_e32 v1, s84, v210
	s_add_i32 s85, 0, 0x1c000
	ds_read_b128 v[110:113], v1
	ds_read_b128 v[114:117], v1 offset:1024
	ds_read_b128 v[122:125], v1 offset:2048
	ds_read_b128 v[126:129], v1 offset:3072
	v_add_u32_e32 v1, s85, v210
	ds_read_b128 v[146:149], v1
	ds_read_b128 v[150:153], v1 offset:1024
	ds_read_b128 v[154:157], v1 offset:2048
	ds_read_b128 v[158:161], v1 offset:3072
	s_add_u32 s50, s50, 0x40000
	s_addc_u32 s51, s51, 0
	s_mov_b32 m0, s74
	ds_read_b128 v[162:165], v221 offset:32768
	ds_read_b128 v[166:169], v221 offset:33792
	ds_read_b128 v[194:197], v221 offset:34816
	ds_read_b128 v[198:201], v221 offset:35840
	ds_read_b128 v[202:205], v221 offset:36864
	ds_read_b128 v[206:209], v221 offset:37888
	ds_read_b128 v[224:227], v221 offset:38912
	ds_read_b128 v[228:231], v221 offset:39936
	global_load_lds_dwordx4 v174, s[50:51]
	s_mov_b32 m0, s75
	s_nop 0
	global_load_lds_dwordx4 v178, s[50:51]
	s_waitcnt vmcnt(8)
	s_waitcnt lgkmcnt(0)
	s_barrier
	s_setprio 1
	v_mfma_f32_16x16x32_bf16 v[62:65], v[110:113], v[162:165], v[62:65]
	v_mfma_f32_16x16x32_bf16 v[42:45], v[122:125], v[162:165], v[42:45]
	v_mfma_f32_16x16x32_bf16 v[50:53], v[110:113], v[194:197], v[50:53]
	v_mfma_f32_16x16x32_bf16 v[38:41], v[122:125], v[194:197], v[38:41]
	v_mfma_f32_16x16x32_bf16 v[46:49], v[110:113], v[202:205], v[46:49]
	v_mfma_f32_16x16x32_bf16 v[34:37], v[122:125], v[202:205], v[34:37]
	v_mfma_f32_16x16x32_bf16 v[142:145], v[110:113], v[224:227], v[142:145]
	v_mfma_f32_16x16x32_bf16 v[82:85], v[122:125], v[224:227], v[82:85]
	v_mfma_f32_16x16x32_bf16 v[62:65], v[114:117], v[166:169], v[62:65]
	v_mfma_f32_16x16x32_bf16 v[42:45], v[126:129], v[166:169], v[42:45]
	v_mfma_f32_16x16x32_bf16 v[50:53], v[114:117], v[198:201], v[50:53]
	v_mfma_f32_16x16x32_bf16 v[38:41], v[126:129], v[198:201], v[38:41]
	v_mfma_f32_16x16x32_bf16 v[46:49], v[114:117], v[206:209], v[46:49]
	v_mfma_f32_16x16x32_bf16 v[34:37], v[126:129], v[206:209], v[34:37]
	v_mfma_f32_16x16x32_bf16 v[142:145], v[114:117], v[228:231], v[142:145]
	v_mfma_f32_16x16x32_bf16 v[82:85], v[126:129], v[228:231], v[82:85]
	v_mfma_f32_16x16x32_bf16 v[134:137], v[146:149], v[162:165], v[134:137]
	v_mfma_f32_16x16x32_bf16 v[74:77], v[154:157], v[162:165], v[74:77]
	v_mfma_f32_16x16x32_bf16 v[130:133], v[146:149], v[194:197], v[130:133]
	v_mfma_f32_16x16x32_bf16 v[70:73], v[154:157], v[194:197], v[70:73]
	v_mfma_f32_16x16x32_bf16 v[78:81], v[146:149], v[202:205], v[78:81]
	v_mfma_f32_16x16x32_bf16 v[66:69], v[154:157], v[202:205], v[66:69]
	v_mfma_f32_16x16x32_bf16 v[138:141], v[146:149], v[224:227], v[138:141]
	v_mfma_f32_16x16x32_bf16 v[98:101], v[154:157], v[224:227], v[98:101]
	v_mfma_f32_16x16x32_bf16 v[134:137], v[150:153], v[166:169], v[134:137]
	v_mfma_f32_16x16x32_bf16 v[74:77], v[158:161], v[166:169], v[74:77]
	v_mfma_f32_16x16x32_bf16 v[130:133], v[150:153], v[198:201], v[130:133]
	v_mfma_f32_16x16x32_bf16 v[70:73], v[158:161], v[198:201], v[70:73]
	v_mfma_f32_16x16x32_bf16 v[78:81], v[150:153], v[206:209], v[78:81]
	v_mfma_f32_16x16x32_bf16 v[66:69], v[158:161], v[206:209], v[66:69]
	v_mfma_f32_16x16x32_bf16 v[138:141], v[150:153], v[228:231], v[138:141]
	v_mfma_f32_16x16x32_bf16 v[98:101], v[158:161], v[228:231], v[98:101]
	s_setprio 0
	s_barrier
	s_add_i32 s50, s84, s64
	s_mov_b32 m0, s50
	ds_read_b128 v[162:165], v221 offset:49152
	ds_read_b128 v[166:169], v221 offset:50176
	ds_read_b128 v[194:197], v221 offset:51200
	ds_read_b128 v[198:201], v221 offset:52224
	ds_read_b128 v[202:205], v221 offset:53248
	ds_read_b128 v[206:209], v221 offset:54272
	ds_read_b128 v[224:227], v221 offset:55296
	ds_read_b128 v[228:231], v221 offset:56320
	global_load_lds_dwordx4 v176, s[98:99]
	s_add_i32 m0, s50, 0x2000
	s_add_u32 s48, s48, 0x40080
	s_addc_u32 s49, s49, 0
	s_add_i32 s50, s85, s64
	global_load_lds_dwordx4 v180, s[98:99]
	s_mov_b32 m0, s50
	s_nop 0
	global_load_lds_dwordx4 v176, s[48:49]
	s_add_i32 m0, s50, 0x2000
	s_nop 0
	global_load_lds_dwordx4 v180, s[48:49]
	s_mov_b32 m0, s77
	s_nop 0
	global_load_lds_dwordx4 v174, s[100:101]
	s_mov_b32 m0, s78
	s_nop 0
	global_load_lds_dwordx4 v178, s[100:101]
	s_waitcnt vmcnt(8)
	s_waitcnt lgkmcnt(0)
	s_barrier
	s_setprio 1
	v_mfma_f32_16x16x32_bf16 v[94:97], v[110:113], v[162:165], v[94:97]
	v_mfma_f32_16x16x32_bf16 v[10:13], v[122:125], v[162:165], v[10:13]
	v_mfma_f32_16x16x32_bf16 v[90:93], v[110:113], v[194:197], v[90:93]
	v_mfma_f32_16x16x32_bf16 v[6:9], v[122:125], v[194:197], v[6:9]
	v_mfma_f32_16x16x32_bf16 v[86:89], v[110:113], v[202:205], v[86:89]
	v_mfma_f32_16x16x32_bf16 v[2:5], v[122:125], v[202:205], v[2:5]
	v_mfma_f32_16x16x32_bf16 v[30:33], v[110:113], v[224:227], v[30:33]
	v_mfma_f32_16x16x32_bf16 v[26:29], v[122:125], v[224:227], v[26:29]
	v_mfma_f32_16x16x32_bf16 v[94:97], v[114:117], v[166:169], v[94:97]
	v_mfma_f32_16x16x32_bf16 v[10:13], v[126:129], v[166:169], v[10:13]
	v_mfma_f32_16x16x32_bf16 v[90:93], v[114:117], v[198:201], v[90:93]
	v_mfma_f32_16x16x32_bf16 v[6:9], v[126:129], v[198:201], v[6:9]
	v_mfma_f32_16x16x32_bf16 v[86:89], v[114:117], v[206:209], v[86:89]
	v_mfma_f32_16x16x32_bf16 v[2:5], v[126:129], v[206:209], v[2:5]
	v_mfma_f32_16x16x32_bf16 v[114:117], v[114:117], v[228:231], v[30:33]
	v_mfma_f32_16x16x32_bf16 v[26:29], v[126:129], v[228:231], v[26:29]
	v_mfma_f32_16x16x32_bf16 v[30:33], v[146:149], v[162:165], v[54:57]
	v_mfma_f32_16x16x32_bf16 v[110:113], v[150:153], v[166:169], v[30:33]
	v_mfma_f32_16x16x32_bf16 v[30:33], v[146:149], v[194:197], v[106:109]
	v_mfma_f32_16x16x32_bf16 v[106:109], v[150:153], v[198:201], v[30:33]
	v_mfma_f32_16x16x32_bf16 v[30:33], v[146:149], v[202:205], v[102:105]
	v_mfma_f32_16x16x32_bf16 v[102:105], v[150:153], v[206:209], v[30:33]
	v_mfma_f32_16x16x32_bf16 v[30:33], v[146:149], v[224:227], v[118:121]
	v_mfma_f32_16x16x32_bf16 v[22:25], v[154:157], v[162:165], v[22:25]
	v_mfma_f32_16x16x32_bf16 v[18:21], v[154:157], v[194:197], v[18:21]
	v_mfma_f32_16x16x32_bf16 v[14:17], v[154:157], v[202:205], v[14:17]
	v_mfma_f32_16x16x32_bf16 v[126:129], v[150:153], v[228:231], v[30:33]
	v_mfma_f32_16x16x32_bf16 v[30:33], v[154:157], v[224:227], v[58:61]
	v_mfma_f32_16x16x32_bf16 v[22:25], v[158:161], v[166:169], v[22:25]
	v_mfma_f32_16x16x32_bf16 v[18:21], v[158:161], v[198:201], v[18:21]
	v_mfma_f32_16x16x32_bf16 v[14:17], v[158:161], v[206:209], v[14:17]
	v_mfma_f32_16x16x32_bf16 v[58:61], v[158:161], v[228:231], v[30:33]
	s_setprio 0
	s_barrier
	s_add_i32 s7, s7, 2
	s_add_u32 s8, s8, 0x100
	s_addc_u32 s9, s9, 0
	s_add_u32 vcc_hi, vcc_hi, 0x100
	s_addc_u32 s3, s3, 0
	s_cmp_gt_u32 s7, 13
	s_cbranch_scc0 .LBB0_557
	s_and_b64 vcc, exec, s[14:15]
	s_cbranch_vccz .LBB0_560
	s_nop 0
.LBB0_560:
	s_mov_b32 s98, 1.0
	s_mov_b32 s99, 1.0
	s_mov_b32 s100, 0xbfb8aa3b
	s_mov_b32 s101, 0xbfb8aa3b
	v_readfirstlane_b32 s50, v170
	v_and_b32_e32 v224, 15, v170
	v_bfe_u32 v245, v170, 4, 2
	s_lshr_b32 s50, s50, 6
	s_and_b32 s51, s50, 3
	s_lshr_b32 s50, s50, 2
	s_lshl_b32 s51, s51, 7
	v_lshl_add_u32 v225, v245, 5, s51
	s_bitcmp1_b32 s29, 0
	s_cselect_b32 s3, 0x1800, 0
	s_add_i32 s3, s3, 0x22100
	v_add_u32_e32 v226, s3, v225
	s_lshl_b32 s51, s50, 8
	s_add_i32 s51, s51, s3
	v_lshl_add_u32 v245, v224, 4, s51
	ds_read_b128 v[146:149], v245 offset:4096
	ds_read_b128 v[150:153], v245 offset:4608
	ds_read_b128 v[154:157], v226 offset:5120
	ds_read_b128 v[158:161], v226 offset:5136
	ds_read_b128 v[162:165], v226 offset:5632
	ds_read_b128 v[166:169], v226 offset:5648
	ds_read_b128 v[194:197], v226 offset:512
	ds_read_b128 v[198:201], v226 offset:1536
	ds_read_b128 v[202:205], v226 offset:2560
	ds_read_b128 v[206:209], v226 offset:3584
	s_lshl_b32 s51, s50, 11
	s_add_i32 s51, s51, 0x1f800
	v_add_u32_e32 v227, s51, v225
	s_mul_i32 s51, s28, 0xb000
	s_lshl_b32 s3, s46, 9
	s_add_i32 s51, s51, s3
	v_add_u32_e32 v228, s51, v225
	v_add_u32_e32 v229, 0x2c00, v228
	v_add_u32_e32 v230, 0x5800, v228
	v_add_u32_e32 v231, 0x8400, v228
	s_lshl_b32 s51, s28, 8
	s_lshl_b32 s3, s50, 6
	s_add_i32 s51, s51, s3
	v_lshl_add_u32 v244, v224, 2, s51
	v_mul_u32_u24_e32 v244, 0x1600, v244
	s_lshl_b32 s3, s46, 8
	v_lshrrev_b32_e32 v245, 1, v225
	v_add3_u32 v244, v244, v245, s3
	v_mov_b32_e32 v245, 0x358637bd
	s_waitcnt lgkmcnt(8)
	v_fmamk_f32 v146, v146, 0x3a800000, v245
	v_fmamk_f32 v147, v147, 0x3a800000, v245
	v_fmamk_f32 v148, v148, 0x3a800000, v245
	v_fmamk_f32 v149, v149, 0x3a800000, v245
	v_fmamk_f32 v150, v150, 0x3a800000, v245
	v_fmamk_f32 v151, v151, 0x3a800000, v245
	v_fmamk_f32 v152, v152, 0x3a800000, v245
	v_fmamk_f32 v153, v153, 0x3a800000, v245
	v_rsq_f32_e32 v146, v146
	v_rsq_f32_e32 v147, v147
	v_rsq_f32_e32 v148, v148
	v_rsq_f32_e32 v149, v149
	v_rsq_f32_e32 v150, v150
	v_rsq_f32_e32 v151, v151
	v_rsq_f32_e32 v152, v152
	v_rsq_f32_e32 v153, v153
	s_waitcnt lgkmcnt(4)
	v_pk_fma_f32 v[62:63], v[62:63], v[146:147], v[154:155] op_sel:[0,0,0] op_sel_hi:[1,0,1]
	v_pk_fma_f32 v[64:65], v[64:65], v[146:147], v[156:157] op_sel:[0,0,0] op_sel_hi:[1,0,1]
	v_pk_fma_f32 v[42:43], v[42:43], v[146:147], v[158:159] op_sel:[0,0,0] op_sel_hi:[1,0,1]
	v_pk_fma_f32 v[44:45], v[44:45], v[146:147], v[160:161] op_sel:[0,0,0] op_sel_hi:[1,0,1]
	v_pk_fma_f32 v[134:135], v[134:135], v[146:147], v[162:163] op_sel:[0,0,0] op_sel_hi:[1,0,1]
	v_pk_fma_f32 v[136:137], v[136:137], v[146:147], v[164:165] op_sel:[0,0,0] op_sel_hi:[1,0,1]
	v_pk_fma_f32 v[74:75], v[74:75], v[146:147], v[166:167] op_sel:[0,0,0] op_sel_hi:[1,0,1]
	v_pk_fma_f32 v[76:77], v[76:77], v[146:147], v[168:169] op_sel:[0,0,0] op_sel_hi:[1,0,1]
	v_pk_fma_f32 v[50:51], v[50:51], v[146:147], v[154:155] op_sel:[0,1,0] op_sel_hi:[1,1,1]
	v_pk_fma_f32 v[52:53], v[52:53], v[146:147], v[156:157] op_sel:[0,1,0] op_sel_hi:[1,1,1]
	v_pk_fma_f32 v[38:39], v[38:39], v[146:147], v[158:159] op_sel:[0,1,0] op_sel_hi:[1,1,1]
	v_pk_fma_f32 v[40:41], v[40:41], v[146:147], v[160:161] op_sel:[0,1,0] op_sel_hi:[1,1,1]
	v_pk_fma_f32 v[130:131], v[130:131], v[146:147], v[162:163] op_sel:[0,1,0] op_sel_hi:[1,1,1]
	v_pk_fma_f32 v[132:133], v[132:133], v[146:147], v[164:165] op_sel:[0,1,0] op_sel_hi:[1,1,1]
	v_pk_fma_f32 v[70:71], v[70:71], v[146:147], v[166:167] op_sel:[0,1,0] op_sel_hi:[1,1,1]
	v_pk_fma_f32 v[72:73], v[72:73], v[146:147], v[168:169] op_sel:[0,1,0] op_sel_hi:[1,1,1]
	v_pk_fma_f32 v[46:47], v[46:47], v[148:149], v[154:155] op_sel:[0,0,0] op_sel_hi:[1,0,1]
	v_pk_fma_f32 v[48:49], v[48:49], v[148:149], v[156:157] op_sel:[0,0,0] op_sel_hi:[1,0,1]
	v_pk_fma_f32 v[34:35], v[34:35], v[148:149], v[158:159] op_sel:[0,0,0] op_sel_hi:[1,0,1]
	v_pk_fma_f32 v[36:37], v[36:37], v[148:149], v[160:161] op_sel:[0,0,0] op_sel_hi:[1,0,1]
	v_pk_fma_f32 v[78:79], v[78:79], v[148:149], v[162:163] op_sel:[0,0,0] op_sel_hi:[1,0,1]
	v_pk_fma_f32 v[80:81], v[80:81], v[148:149], v[164:165] op_sel:[0,0,0] op_sel_hi:[1,0,1]
	v_pk_fma_f32 v[66:67], v[66:67], v[148:149], v[166:167] op_sel:[0,0,0] op_sel_hi:[1,0,1]
	v_pk_fma_f32 v[68:69], v[68:69], v[148:149], v[168:169] op_sel:[0,0,0] op_sel_hi:[1,0,1]
	v_pk_fma_f32 v[142:143], v[142:143], v[148:149], v[154:155] op_sel:[0,1,0] op_sel_hi:[1,1,1]
	v_pk_fma_f32 v[144:145], v[144:145], v[148:149], v[156:157] op_sel:[0,1,0] op_sel_hi:[1,1,1]
	v_pk_fma_f32 v[82:83], v[82:83], v[148:149], v[158:159] op_sel:[0,1,0] op_sel_hi:[1,1,1]
	v_pk_fma_f32 v[84:85], v[84:85], v[148:149], v[160:161] op_sel:[0,1,0] op_sel_hi:[1,1,1]
	v_pk_fma_f32 v[138:139], v[138:139], v[148:149], v[162:163] op_sel:[0,1,0] op_sel_hi:[1,1,1]
	v_pk_fma_f32 v[140:141], v[140:141], v[148:149], v[164:165] op_sel:[0,1,0] op_sel_hi:[1,1,1]
	v_pk_fma_f32 v[98:99], v[98:99], v[148:149], v[166:167] op_sel:[0,1,0] op_sel_hi:[1,1,1]
	v_pk_fma_f32 v[100:101], v[100:101], v[148:149], v[168:169] op_sel:[0,1,0] op_sel_hi:[1,1,1]
	v_pk_fma_f32 v[94:95], v[94:95], v[150:151], v[154:155] op_sel:[0,0,0] op_sel_hi:[1,0,1]
	v_pk_fma_f32 v[96:97], v[96:97], v[150:151], v[156:157] op_sel:[0,0,0] op_sel_hi:[1,0,1]
	v_pk_fma_f32 v[10:11], v[10:11], v[150:151], v[158:159] op_sel:[0,0,0] op_sel_hi:[1,0,1]
	v_pk_fma_f32 v[12:13], v[12:13], v[150:151], v[160:161] op_sel:[0,0,0] op_sel_hi:[1,0,1]
	v_pk_fma_f32 v[110:111], v[110:111], v[150:151], v[162:163] op_sel:[0,0,0] op_sel_hi:[1,0,1]
	v_pk_fma_f32 v[112:113], v[112:113], v[150:151], v[164:165] op_sel:[0,0,0] op_sel_hi:[1,0,1]
	v_pk_fma_f32 v[22:23], v[22:23], v[150:151], v[166:167] op_sel:[0,0,0] op_sel_hi:[1,0,1]
	v_pk_fma_f32 v[24:25], v[24:25], v[150:151], v[168:169] op_sel:[0,0,0] op_sel_hi:[1,0,1]
	v_pk_fma_f32 v[90:91], v[90:91], v[150:151], v[154:155] op_sel:[0,1,0] op_sel_hi:[1,1,1]
	v_pk_fma_f32 v[92:93], v[92:93], v[150:151], v[156:157] op_sel:[0,1,0] op_sel_hi:[1,1,1]
	v_pk_fma_f32 v[6:7], v[6:7], v[150:151], v[158:159] op_sel:[0,1,0] op_sel_hi:[1,1,1]
	v_pk_fma_f32 v[8:9], v[8:9], v[150:151], v[160:161] op_sel:[0,1,0] op_sel_hi:[1,1,1]
	v_pk_fma_f32 v[106:107], v[106:107], v[150:151], v[162:163] op_sel:[0,1,0] op_sel_hi:[1,1,1]
	v_pk_fma_f32 v[108:109], v[108:109], v[150:151], v[164:165] op_sel:[0,1,0] op_sel_hi:[1,1,1]
	v_pk_fma_f32 v[18:19], v[18:19], v[150:151], v[166:167] op_sel:[0,1,0] op_sel_hi:[1,1,1]
	v_pk_fma_f32 v[20:21], v[20:21], v[150:151], v[168:169] op_sel:[0,1,0] op_sel_hi:[1,1,1]
	v_pk_fma_f32 v[86:87], v[86:87], v[152:153], v[154:155] op_sel:[0,0,0] op_sel_hi:[1,0,1]
	v_pk_fma_f32 v[88:89], v[88:89], v[152:153], v[156:157] op_sel:[0,0,0] op_sel_hi:[1,0,1]
	v_pk_fma_f32 v[2:3], v[2:3], v[152:153], v[158:159] op_sel:[0,0,0] op_sel_hi:[1,0,1]
	v_pk_fma_f32 v[4:5], v[4:5], v[152:153], v[160:161] op_sel:[0,0,0] op_sel_hi:[1,0,1]
	v_pk_fma_f32 v[102:103], v[102:103], v[152:153], v[162:163] op_sel:[0,0,0] op_sel_hi:[1,0,1]
	v_pk_fma_f32 v[104:105], v[104:105], v[152:153], v[164:165] op_sel:[0,0,0] op_sel_hi:[1,0,1]
	v_pk_fma_f32 v[14:15], v[14:15], v[152:153], v[166:167] op_sel:[0,0,0] op_sel_hi:[1,0,1]
	v_pk_fma_f32 v[16:17], v[16:17], v[152:153], v[168:169] op_sel:[0,0,0] op_sel_hi:[1,0,1]
	v_pk_fma_f32 v[114:115], v[114:115], v[152:153], v[154:155] op_sel:[0,1,0] op_sel_hi:[1,1,1]
	v_pk_fma_f32 v[116:117], v[116:117], v[152:153], v[156:157] op_sel:[0,1,0] op_sel_hi:[1,1,1]
	v_pk_fma_f32 v[26:27], v[26:27], v[152:153], v[158:159] op_sel:[0,1,0] op_sel_hi:[1,1,1]
	v_pk_fma_f32 v[28:29], v[28:29], v[152:153], v[160:161] op_sel:[0,1,0] op_sel_hi:[1,1,1]
	v_pk_fma_f32 v[126:127], v[126:127], v[152:153], v[162:163] op_sel:[0,1,0] op_sel_hi:[1,1,1]
	v_pk_fma_f32 v[128:129], v[128:129], v[152:153], v[164:165] op_sel:[0,1,0] op_sel_hi:[1,1,1]
	v_pk_fma_f32 v[58:59], v[58:59], v[152:153], v[166:167] op_sel:[0,1,0] op_sel_hi:[1,1,1]
	v_pk_fma_f32 v[60:61], v[60:61], v[152:153], v[168:169] op_sel:[0,1,0] op_sel_hi:[1,1,1]
	v_cmp_eq_u32_e32 vcc, 15, v224
	s_and_saveexec_b64 s[8:9], vcc
	ds_write_b128 v227, v[46:49] offset:2048
	ds_write_b128 v227, v[34:37] offset:2064
	ds_write_b128 v227, v[78:81] offset:2560
	ds_write_b128 v227, v[66:69] offset:2576
	ds_write_b128 v227, v[142:145] offset:3072
	ds_write_b128 v227, v[82:85] offset:3088
	ds_write_b128 v227, v[138:141] offset:3584
	ds_write_b128 v227, v[98:101] offset:3600
	ds_write_b128 v227, v[86:89] offset:6144
	ds_write_b128 v227, v[2:5] offset:6160
	ds_write_b128 v227, v[102:105] offset:6656
	ds_write_b128 v227, v[14:17] offset:6672
	ds_write_b128 v227, v[114:117] offset:7168
	ds_write_b128 v227, v[26:29] offset:7184
	ds_write_b128 v227, v[126:129] offset:7680
	ds_write_b128 v227, v[58:61] offset:7696
	s_cmp_lg_u32 s50, 1
	s_cbranch_scc1 .Lnepia_nohalo
	s_add_u32 s48, s88, 0x2a00000
	s_addc_u32 s49, s89, 0
	global_store_dwordx4 v228, v[86:89], s[48:49] offset:0
	global_store_dwordx4 v228, v[2:5], s[48:49] offset:16
	global_store_dwordx4 v229, v[102:105], s[48:49] offset:0
	global_store_dwordx4 v229, v[14:17], s[48:49] offset:16
	global_store_dwordx4 v230, v[114:117], s[48:49] offset:0
	global_store_dwordx4 v230, v[26:29], s[48:49] offset:16
	global_store_dwordx4 v231, v[126:129], s[48:49] offset:0
	global_store_dwordx4 v231, v[58:61], s[48:49] offset:16
.Lnepia_nohalo:
	s_or_b64 exec, exec, s[8:9]
	s_cmp_lg_u32 s50, 0
	s_cbranch_scc1 .Lnepia_noalign
	s_barrier
.Lnepia_noalign:
	s_waitcnt lgkmcnt(0)
	s_barrier
	s_cmp_eq_u32 s50, 0
	s_cbranch_scc1 .Lnepia_z0
	ds_read_b128 v[118:121], v227 offset:512
	ds_read_b128 v[122:125], v227 offset:1536
	s_branch .Lnepia_j0

.LBB0_1317:
	ds_read_b128 v[30:33], v219
	ds_read_b128 v[54:57], v219 offset:1024
	ds_read_b128 v[118:121], v219 offset:2048
	ds_read_b128 v[122:125], v219 offset:3072
	ds_read_b128 v[146:149], v220
	ds_read_b128 v[150:153], v220 offset:1024
	ds_read_b128 v[154:157], v220 offset:2048
	ds_read_b128 v[158:161], v220 offset:3072
	s_add_u32 s52, s8, 0xfffc0080
	s_addc_u32 s53, s9, -1
	s_cmp_eq_u32 s93, 12
	s_cselect_b32 s55, s45, s53
	s_cselect_b32 s54, s51, s52
	s_cselect_b32 s53, s43, s92
	s_cselect_b32 s52, s90, s91
	s_add_i32 m0, s59, 0xc000
	ds_read_b128 v[162:165], v221
	ds_read_b128 v[166:169], v221 offset:1024
	ds_read_b128 v[196:199], v221 offset:2048
	ds_read_b128 v[200:203], v221 offset:3072
	ds_read_b128 v[204:207], v221 offset:4096
	ds_read_b128 v[208:211], v221 offset:5120
	ds_read_b128 v[224:227], v221 offset:6144
	ds_read_b128 v[228:231], v221 offset:7168
	global_load_lds_dwordx4 v188, s[8:9]
	s_add_i32 m0, s59, 0xe000
	s_nop 0
	global_load_lds_dwordx4 v190, s[8:9]
	s_waitcnt vmcnt(8)
	s_waitcnt lgkmcnt(0)
	s_barrier
	s_setprio 1
	v_mfma_f32_16x16x32_bf16 v[62:65], v[30:33], v[162:165], v[62:65]
	v_mfma_f32_16x16x32_bf16 v[42:45], v[118:121], v[162:165], v[42:45]
	v_mfma_f32_16x16x32_bf16 v[50:53], v[30:33], v[196:199], v[50:53]
	v_mfma_f32_16x16x32_bf16 v[38:41], v[118:121], v[196:199], v[38:41]
	v_mfma_f32_16x16x32_bf16 v[46:49], v[30:33], v[204:207], v[46:49]
	v_mfma_f32_16x16x32_bf16 v[34:37], v[118:121], v[204:207], v[34:37]
	v_mfma_f32_16x16x32_bf16 v[142:145], v[30:33], v[224:227], v[142:145]
	v_mfma_f32_16x16x32_bf16 v[82:85], v[118:121], v[224:227], v[82:85]
	v_mfma_f32_16x16x32_bf16 v[62:65], v[54:57], v[166:169], v[62:65]
	v_mfma_f32_16x16x32_bf16 v[42:45], v[122:125], v[166:169], v[42:45]
	v_mfma_f32_16x16x32_bf16 v[50:53], v[54:57], v[200:203], v[50:53]
	v_mfma_f32_16x16x32_bf16 v[38:41], v[122:125], v[200:203], v[38:41]
	v_mfma_f32_16x16x32_bf16 v[46:49], v[54:57], v[208:211], v[46:49]
	v_mfma_f32_16x16x32_bf16 v[34:37], v[122:125], v[208:211], v[34:37]
	v_mfma_f32_16x16x32_bf16 v[142:145], v[54:57], v[228:231], v[142:145]
	v_mfma_f32_16x16x32_bf16 v[82:85], v[122:125], v[228:231], v[82:85]
	v_mfma_f32_16x16x32_bf16 v[134:137], v[146:149], v[162:165], v[134:137]
	v_mfma_f32_16x16x32_bf16 v[74:77], v[154:157], v[162:165], v[74:77]
	v_mfma_f32_16x16x32_bf16 v[130:133], v[146:149], v[196:199], v[130:133]
	v_mfma_f32_16x16x32_bf16 v[70:73], v[154:157], v[196:199], v[70:73]
	v_mfma_f32_16x16x32_bf16 v[78:81], v[146:149], v[204:207], v[78:81]
	v_mfma_f32_16x16x32_bf16 v[66:69], v[154:157], v[204:207], v[66:69]
	v_mfma_f32_16x16x32_bf16 v[138:141], v[146:149], v[224:227], v[138:141]
	v_mfma_f32_16x16x32_bf16 v[98:101], v[154:157], v[224:227], v[98:101]
	v_mfma_f32_16x16x32_bf16 v[134:137], v[150:153], v[166:169], v[134:137]
	v_mfma_f32_16x16x32_bf16 v[74:77], v[158:161], v[166:169], v[74:77]
	v_mfma_f32_16x16x32_bf16 v[130:133], v[150:153], v[200:203], v[130:133]
	v_mfma_f32_16x16x32_bf16 v[70:73], v[158:161], v[200:203], v[70:73]
	v_mfma_f32_16x16x32_bf16 v[78:81], v[150:153], v[208:211], v[78:81]
	v_mfma_f32_16x16x32_bf16 v[66:69], v[158:161], v[208:211], v[66:69]
	v_mfma_f32_16x16x32_bf16 v[138:141], v[150:153], v[228:231], v[138:141]
	v_mfma_f32_16x16x32_bf16 v[98:101], v[158:161], v[228:231], v[98:101]
	s_setprio 0
	s_barrier
	s_add_u32 s98, s52, 0x80
	s_addc_u32 s99, s53, 0
	s_add_u32 s100, s54, 0x80
	s_addc_u32 s101, s55, 0
	s_add_i32 s84, s75, s57
	s_mov_b32 m0, s84
	ds_read_b128 v[162:165], v221 offset:16384
	ds_read_b128 v[166:169], v221 offset:17408
	ds_read_b128 v[196:199], v221 offset:18432
	ds_read_b128 v[200:203], v221 offset:19456
	ds_read_b128 v[204:207], v221 offset:20480
	ds_read_b128 v[208:211], v221 offset:21504
	ds_read_b128 v[224:227], v221 offset:22528
	ds_read_b128 v[228:231], v221 offset:23552
	global_load_lds_dwordx4 v178, s[52:53]
	s_add_i32 m0, s84, 0x2000
	s_add_u32 s84, s52, 0x40000
	s_addc_u32 s85, s53, 0
	s_add_i32 s86, s76, s57
	global_load_lds_dwordx4 v182, s[52:53]
	s_mov_b32 m0, s86
	s_nop 0
	global_load_lds_dwordx4 v178, s[84:85]
	s_add_i32 m0, s86, 0x2000
	s_nop 0
	global_load_lds_dwordx4 v182, s[84:85]
	s_mov_b32 m0, s59
	s_nop 0
	global_load_lds_dwordx4 v176, s[54:55]
	s_mov_b32 m0, s62
	s_nop 0
	global_load_lds_dwordx4 v180, s[54:55]
	s_waitcnt vmcnt(8)
	s_waitcnt lgkmcnt(0)
	s_barrier
	s_setprio 1
	v_mfma_f32_16x16x32_bf16 v[94:97], v[30:33], v[162:165], v[94:97]
	v_mfma_f32_16x16x32_bf16 v[10:13], v[118:121], v[162:165], v[10:13]
	v_mfma_f32_16x16x32_bf16 v[90:93], v[30:33], v[196:199], v[90:93]
	v_mfma_f32_16x16x32_bf16 v[6:9], v[118:121], v[196:199], v[6:9]
	v_mfma_f32_16x16x32_bf16 v[86:89], v[30:33], v[204:207], v[86:89]
	v_mfma_f32_16x16x32_bf16 v[2:5], v[118:121], v[204:207], v[2:5]
	v_mfma_f32_16x16x32_bf16 v[26:29], v[118:121], v[224:227], v[26:29]
	v_mfma_f32_16x16x32_bf16 v[94:97], v[54:57], v[166:169], v[94:97]
	v_mfma_f32_16x16x32_bf16 v[10:13], v[122:125], v[166:169], v[10:13]
	v_mfma_f32_16x16x32_bf16 v[90:93], v[54:57], v[200:203], v[90:93]
	v_mfma_f32_16x16x32_bf16 v[6:9], v[122:125], v[200:203], v[6:9]
	v_mfma_f32_16x16x32_bf16 v[86:89], v[54:57], v[208:211], v[86:89]
	v_mfma_f32_16x16x32_bf16 v[2:5], v[122:125], v[208:211], v[2:5]
	v_mfma_f32_16x16x32_bf16 v[30:33], v[30:33], v[224:227], v[114:117]
	v_mfma_f32_16x16x32_bf16 v[26:29], v[122:125], v[228:231], v[26:29]
	v_mfma_f32_16x16x32_bf16 v[30:33], v[54:57], v[228:231], v[30:33]
	v_mfma_f32_16x16x32_bf16 v[22:25], v[154:157], v[162:165], v[22:25]
	v_mfma_f32_16x16x32_bf16 v[106:109], v[146:149], v[196:199], v[106:109]
	v_mfma_f32_16x16x32_bf16 v[18:21], v[154:157], v[196:199], v[18:21]
	v_mfma_f32_16x16x32_bf16 v[102:105], v[146:149], v[204:207], v[102:105]
	v_mfma_f32_16x16x32_bf16 v[14:17], v[154:157], v[204:207], v[14:17]
	v_mfma_f32_16x16x32_bf16 v[58:61], v[154:157], v[224:227], v[58:61]
	v_mfma_f32_16x16x32_bf16 v[54:57], v[146:149], v[162:165], v[110:113]
	v_mfma_f32_16x16x32_bf16 v[22:25], v[158:161], v[166:169], v[22:25]
	v_mfma_f32_16x16x32_bf16 v[106:109], v[150:153], v[200:203], v[106:109]
	v_mfma_f32_16x16x32_bf16 v[18:21], v[158:161], v[200:203], v[18:21]
	v_mfma_f32_16x16x32_bf16 v[102:105], v[150:153], v[208:211], v[102:105]
	v_mfma_f32_16x16x32_bf16 v[14:17], v[158:161], v[208:211], v[14:17]
	v_mfma_f32_16x16x32_bf16 v[110:113], v[146:149], v[224:227], v[126:129]
	v_mfma_f32_16x16x32_bf16 v[58:61], v[158:161], v[228:231], v[58:61]
	v_mfma_f32_16x16x32_bf16 v[54:57], v[150:153], v[166:169], v[54:57]
	v_mfma_f32_16x16x32_bf16 v[118:121], v[150:153], v[228:231], v[110:113]
	s_setprio 0
	s_barrier
	s_add_i32 s84, 0, 0x18000
	s_add_i32 s85, 0, 0x1c000
	v_add_u32_e32 v126, s84, v175
	v_add_u32_e32 v158, s85, v175
	ds_read_b128 v[110:113], v126
	ds_read_b128 v[114:117], v126 offset:1024
	ds_read_b128 v[122:125], v126 offset:2048
	ds_read_b128 v[126:129], v126 offset:3072
	ds_read_b128 v[146:149], v158
	ds_read_b128 v[150:153], v158 offset:1024
	ds_read_b128 v[154:157], v158 offset:2048
	ds_read_b128 v[158:161], v158 offset:3072
	s_add_u32 s54, s54, 0x40000
	s_addc_u32 s55, s55, 0
	s_mov_b32 m0, s63
	ds_read_b128 v[162:165], v221 offset:32768
	ds_read_b128 v[166:169], v221 offset:33792
	ds_read_b128 v[196:199], v221 offset:34816
	ds_read_b128 v[200:203], v221 offset:35840
	ds_read_b128 v[204:207], v221 offset:36864
	ds_read_b128 v[208:211], v221 offset:37888
	ds_read_b128 v[224:227], v221 offset:38912
	ds_read_b128 v[228:231], v221 offset:39936
	global_load_lds_dwordx4 v176, s[54:55]
	s_mov_b32 m0, s64
	s_nop 0
	global_load_lds_dwordx4 v180, s[54:55]
	s_waitcnt vmcnt(8)
	s_waitcnt lgkmcnt(0)
	s_barrier
	s_setprio 1
	v_mfma_f32_16x16x32_bf16 v[62:65], v[110:113], v[162:165], v[62:65]
	v_mfma_f32_16x16x32_bf16 v[42:45], v[122:125], v[162:165], v[42:45]
	v_mfma_f32_16x16x32_bf16 v[50:53], v[110:113], v[196:199], v[50:53]
	v_mfma_f32_16x16x32_bf16 v[38:41], v[122:125], v[196:199], v[38:41]
	v_mfma_f32_16x16x32_bf16 v[46:49], v[110:113], v[204:207], v[46:49]
	v_mfma_f32_16x16x32_bf16 v[34:37], v[122:125], v[204:207], v[34:37]
	v_mfma_f32_16x16x32_bf16 v[142:145], v[110:113], v[224:227], v[142:145]
	v_mfma_f32_16x16x32_bf16 v[82:85], v[122:125], v[224:227], v[82:85]
	v_mfma_f32_16x16x32_bf16 v[62:65], v[114:117], v[166:169], v[62:65]
	v_mfma_f32_16x16x32_bf16 v[42:45], v[126:129], v[166:169], v[42:45]
	v_mfma_f32_16x16x32_bf16 v[50:53], v[114:117], v[200:203], v[50:53]
	v_mfma_f32_16x16x32_bf16 v[38:41], v[126:129], v[200:203], v[38:41]
	v_mfma_f32_16x16x32_bf16 v[46:49], v[114:117], v[208:211], v[46:49]
	v_mfma_f32_16x16x32_bf16 v[34:37], v[126:129], v[208:211], v[34:37]
	v_mfma_f32_16x16x32_bf16 v[142:145], v[114:117], v[228:231], v[142:145]
	v_mfma_f32_16x16x32_bf16 v[82:85], v[126:129], v[228:231], v[82:85]
	v_mfma_f32_16x16x32_bf16 v[134:137], v[146:149], v[162:165], v[134:137]
	v_mfma_f32_16x16x32_bf16 v[74:77], v[154:157], v[162:165], v[74:77]
	v_mfma_f32_16x16x32_bf16 v[130:133], v[146:149], v[196:199], v[130:133]
	v_mfma_f32_16x16x32_bf16 v[70:73], v[154:157], v[196:199], v[70:73]
	v_mfma_f32_16x16x32_bf16 v[78:81], v[146:149], v[204:207], v[78:81]
	v_mfma_f32_16x16x32_bf16 v[66:69], v[154:157], v[204:207], v[66:69]
	v_mfma_f32_16x16x32_bf16 v[138:141], v[146:149], v[224:227], v[138:141]
	v_mfma_f32_16x16x32_bf16 v[98:101], v[154:157], v[224:227], v[98:101]
	v_mfma_f32_16x16x32_bf16 v[134:137], v[150:153], v[166:169], v[134:137]
	v_mfma_f32_16x16x32_bf16 v[74:77], v[158:161], v[166:169], v[74:77]
	v_mfma_f32_16x16x32_bf16 v[130:133], v[150:153], v[200:203], v[130:133]
	v_mfma_f32_16x16x32_bf16 v[70:73], v[158:161], v[200:203], v[70:73]
	v_mfma_f32_16x16x32_bf16 v[78:81], v[150:153], v[208:211], v[78:81]
	v_mfma_f32_16x16x32_bf16 v[66:69], v[158:161], v[208:211], v[66:69]
	v_mfma_f32_16x16x32_bf16 v[138:141], v[150:153], v[228:231], v[138:141]
	v_mfma_f32_16x16x32_bf16 v[98:101], v[158:161], v[228:231], v[98:101]
	s_setprio 0
	s_barrier
	s_add_i32 s54, s84, s57
	s_mov_b32 m0, s54
	ds_read_b128 v[162:165], v221 offset:49152
	ds_read_b128 v[166:169], v221 offset:50176
	ds_read_b128 v[196:199], v221 offset:51200
	ds_read_b128 v[200:203], v221 offset:52224
	ds_read_b128 v[204:207], v221 offset:53248
	ds_read_b128 v[208:211], v221 offset:54272
	ds_read_b128 v[224:227], v221 offset:55296
	ds_read_b128 v[228:231], v221 offset:56320
	global_load_lds_dwordx4 v178, s[98:99]
	s_add_i32 m0, s54, 0x2000
	s_add_u32 s52, s52, 0x40080
	s_addc_u32 s53, s53, 0
	s_add_i32 s54, s85, s57
	global_load_lds_dwordx4 v182, s[98:99]
	s_mov_b32 m0, s54
	s_nop 0
	global_load_lds_dwordx4 v178, s[52:53]
	s_add_i32 m0, s54, 0x2000
	s_nop 0
	global_load_lds_dwordx4 v182, s[52:53]
	s_mov_b32 m0, s70
	s_nop 0
	global_load_lds_dwordx4 v176, s[100:101]
	s_mov_b32 m0, s71
	s_nop 0
	global_load_lds_dwordx4 v180, s[100:101]
	s_waitcnt vmcnt(8)
	s_waitcnt lgkmcnt(0)
	s_barrier
	s_setprio 1
	v_mfma_f32_16x16x32_bf16 v[94:97], v[110:113], v[162:165], v[94:97]
	v_mfma_f32_16x16x32_bf16 v[10:13], v[122:125], v[162:165], v[10:13]
	v_mfma_f32_16x16x32_bf16 v[90:93], v[110:113], v[196:199], v[90:93]
	v_mfma_f32_16x16x32_bf16 v[6:9], v[122:125], v[196:199], v[6:9]
	v_mfma_f32_16x16x32_bf16 v[86:89], v[110:113], v[204:207], v[86:89]
	v_mfma_f32_16x16x32_bf16 v[2:5], v[122:125], v[204:207], v[2:5]
	v_mfma_f32_16x16x32_bf16 v[30:33], v[110:113], v[224:227], v[30:33]
	v_mfma_f32_16x16x32_bf16 v[26:29], v[122:125], v[224:227], v[26:29]
	v_mfma_f32_16x16x32_bf16 v[94:97], v[114:117], v[166:169], v[94:97]
	v_mfma_f32_16x16x32_bf16 v[10:13], v[126:129], v[166:169], v[10:13]
	v_mfma_f32_16x16x32_bf16 v[90:93], v[114:117], v[200:203], v[90:93]
	v_mfma_f32_16x16x32_bf16 v[6:9], v[126:129], v[200:203], v[6:9]
	v_mfma_f32_16x16x32_bf16 v[86:89], v[114:117], v[208:211], v[86:89]
	v_mfma_f32_16x16x32_bf16 v[2:5], v[126:129], v[208:211], v[2:5]
	v_mfma_f32_16x16x32_bf16 v[114:117], v[114:117], v[228:231], v[30:33]
	v_mfma_f32_16x16x32_bf16 v[26:29], v[126:129], v[228:231], v[26:29]
	v_mfma_f32_16x16x32_bf16 v[30:33], v[146:149], v[162:165], v[54:57]
	v_mfma_f32_16x16x32_bf16 v[110:113], v[150:153], v[166:169], v[30:33]
	v_mfma_f32_16x16x32_bf16 v[30:33], v[146:149], v[196:199], v[106:109]
	v_mfma_f32_16x16x32_bf16 v[106:109], v[150:153], v[200:203], v[30:33]
	v_mfma_f32_16x16x32_bf16 v[30:33], v[146:149], v[204:207], v[102:105]
	v_mfma_f32_16x16x32_bf16 v[102:105], v[150:153], v[208:211], v[30:33]
	v_mfma_f32_16x16x32_bf16 v[30:33], v[146:149], v[224:227], v[118:121]
	v_mfma_f32_16x16x32_bf16 v[22:25], v[154:157], v[162:165], v[22:25]
	v_mfma_f32_16x16x32_bf16 v[18:21], v[154:157], v[196:199], v[18:21]
	v_mfma_f32_16x16x32_bf16 v[14:17], v[154:157], v[204:207], v[14:17]
	v_mfma_f32_16x16x32_bf16 v[126:129], v[150:153], v[228:231], v[30:33]
	v_mfma_f32_16x16x32_bf16 v[30:33], v[154:157], v[224:227], v[58:61]
	v_mfma_f32_16x16x32_bf16 v[22:25], v[158:161], v[166:169], v[22:25]
	v_mfma_f32_16x16x32_bf16 v[18:21], v[158:161], v[200:203], v[18:21]
	v_mfma_f32_16x16x32_bf16 v[14:17], v[158:161], v[208:211], v[14:17]
	v_mfma_f32_16x16x32_bf16 v[58:61], v[158:161], v[228:231], v[30:33]
	s_setprio 0
	s_barrier
	s_add_i32 s93, s93, 2
	s_add_u32 s8, s8, 0x100
	s_addc_u32 s9, s9, 0
	s_add_u32 s91, s91, 0x100
	s_addc_u32 s92, s92, 0
	s_cmp_gt_u32 s93, 13
	s_cbranch_scc0 .LBB0_1317
	s_and_b64 vcc, exec, s[18:19]
	s_cbranch_vccz .LBB0_1320
	s_nop 0
.LBB0_1320:
	s_mov_b32 s98, 1.0
	s_mov_b32 s99, 1.0
	s_mov_b32 s100, 0xbfb8aa3b
	s_mov_b32 s101, 0xbfb8aa3b
	v_readfirstlane_b32 s54, v170
	v_and_b32_e32 v224, 15, v170
	v_bfe_u32 v245, v170, 4, 2
	s_lshr_b32 s54, s54, 6
	s_and_b32 s55, s54, 3
	s_lshr_b32 s54, s54, 2
	s_lshl_b32 s55, s55, 7
	v_lshl_add_u32 v225, v245, 5, s55
	s_bitcmp1_b32 s31, 0
	s_cselect_b32 s51, 0x1800, 0
	s_add_i32 s51, s51, 0x22100
	v_add_u32_e32 v226, s51, v225
	s_lshl_b32 s55, s54, 8
	s_add_i32 s55, s55, s51
	v_lshl_add_u32 v245, v224, 4, s55
	ds_read_b128 v[146:149], v245 offset:4096
	ds_read_b128 v[150:153], v245 offset:4608
	ds_read_b128 v[154:157], v226 offset:5120
	ds_read_b128 v[158:161], v226 offset:5136
	ds_read_b128 v[162:165], v226 offset:5632
	ds_read_b128 v[166:169], v226 offset:5648
	ds_read_b128 v[196:199], v226 offset:512
	ds_read_b128 v[200:203], v226 offset:1536
	ds_read_b128 v[204:207], v226 offset:2560
	ds_read_b128 v[208:211], v226 offset:3584
	s_lshl_b32 s55, s54, 11
	s_add_i32 s55, s55, 0x1f800
	v_add_u32_e32 v227, s55, v225
	s_mul_i32 s55, s30, 0xb000
	s_lshl_b32 s51, s50, 9
	s_add_i32 s55, s55, s51
	v_add_u32_e32 v228, s55, v225
	v_add_u32_e32 v229, 0x2c00, v228
	v_add_u32_e32 v230, 0x5800, v228
	v_add_u32_e32 v231, 0x8400, v228
	s_lshl_b32 s55, s30, 8
	s_lshl_b32 s51, s54, 6
	s_add_i32 s55, s55, s51
	v_lshl_add_u32 v244, v224, 2, s55
	v_mul_u32_u24_e32 v244, 0x1600, v244
	s_lshl_b32 s51, s50, 8
	v_lshrrev_b32_e32 v245, 1, v225
	v_add3_u32 v244, v244, v245, s51
	v_mov_b32_e32 v245, 0x358637bd
	s_waitcnt lgkmcnt(8)
	v_fmamk_f32 v146, v146, 0x3a800000, v245
	v_fmamk_f32 v147, v147, 0x3a800000, v245
	v_fmamk_f32 v148, v148, 0x3a800000, v245
	v_fmamk_f32 v149, v149, 0x3a800000, v245
	v_fmamk_f32 v150, v150, 0x3a800000, v245
	v_fmamk_f32 v151, v151, 0x3a800000, v245
	v_fmamk_f32 v152, v152, 0x3a800000, v245
	v_fmamk_f32 v153, v153, 0x3a800000, v245
	v_rsq_f32_e32 v146, v146
	v_rsq_f32_e32 v147, v147
	v_rsq_f32_e32 v148, v148
	v_rsq_f32_e32 v149, v149
	v_rsq_f32_e32 v150, v150
	v_rsq_f32_e32 v151, v151
	v_rsq_f32_e32 v152, v152
	v_rsq_f32_e32 v153, v153
	s_waitcnt lgkmcnt(4)
	v_pk_fma_f32 v[62:63], v[62:63], v[146:147], v[154:155] op_sel:[0,0,0] op_sel_hi:[1,0,1]
	v_pk_fma_f32 v[64:65], v[64:65], v[146:147], v[156:157] op_sel:[0,0,0] op_sel_hi:[1,0,1]
	v_pk_fma_f32 v[42:43], v[42:43], v[146:147], v[158:159] op_sel:[0,0,0] op_sel_hi:[1,0,1]
	v_pk_fma_f32 v[44:45], v[44:45], v[146:147], v[160:161] op_sel:[0,0,0] op_sel_hi:[1,0,1]
	v_pk_fma_f32 v[134:135], v[134:135], v[146:147], v[162:163] op_sel:[0,0,0] op_sel_hi:[1,0,1]
	v_pk_fma_f32 v[136:137], v[136:137], v[146:147], v[164:165] op_sel:[0,0,0] op_sel_hi:[1,0,1]
	v_pk_fma_f32 v[74:75], v[74:75], v[146:147], v[166:167] op_sel:[0,0,0] op_sel_hi:[1,0,1]
	v_pk_fma_f32 v[76:77], v[76:77], v[146:147], v[168:169] op_sel:[0,0,0] op_sel_hi:[1,0,1]
	v_pk_fma_f32 v[50:51], v[50:51], v[146:147], v[154:155] op_sel:[0,1,0] op_sel_hi:[1,1,1]
	v_pk_fma_f32 v[52:53], v[52:53], v[146:147], v[156:157] op_sel:[0,1,0] op_sel_hi:[1,1,1]
	v_pk_fma_f32 v[38:39], v[38:39], v[146:147], v[158:159] op_sel:[0,1,0] op_sel_hi:[1,1,1]
	v_pk_fma_f32 v[40:41], v[40:41], v[146:147], v[160:161] op_sel:[0,1,0] op_sel_hi:[1,1,1]
	v_pk_fma_f32 v[130:131], v[130:131], v[146:147], v[162:163] op_sel:[0,1,0] op_sel_hi:[1,1,1]
	v_pk_fma_f32 v[132:133], v[132:133], v[146:147], v[164:165] op_sel:[0,1,0] op_sel_hi:[1,1,1]
	v_pk_fma_f32 v[70:71], v[70:71], v[146:147], v[166:167] op_sel:[0,1,0] op_sel_hi:[1,1,1]
	v_pk_fma_f32 v[72:73], v[72:73], v[146:147], v[168:169] op_sel:[0,1,0] op_sel_hi:[1,1,1]
	v_pk_fma_f32 v[46:47], v[46:47], v[148:149], v[154:155] op_sel:[0,0,0] op_sel_hi:[1,0,1]
	v_pk_fma_f32 v[48:49], v[48:49], v[148:149], v[156:157] op_sel:[0,0,0] op_sel_hi:[1,0,1]
	v_pk_fma_f32 v[34:35], v[34:35], v[148:149], v[158:159] op_sel:[0,0,0] op_sel_hi:[1,0,1]
	v_pk_fma_f32 v[36:37], v[36:37], v[148:149], v[160:161] op_sel:[0,0,0] op_sel_hi:[1,0,1]
	v_pk_fma_f32 v[78:79], v[78:79], v[148:149], v[162:163] op_sel:[0,0,0] op_sel_hi:[1,0,1]
	v_pk_fma_f32 v[80:81], v[80:81], v[148:149], v[164:165] op_sel:[0,0,0] op_sel_hi:[1,0,1]
	v_pk_fma_f32 v[66:67], v[66:67], v[148:149], v[166:167] op_sel:[0,0,0] op_sel_hi:[1,0,1]
	v_pk_fma_f32 v[68:69], v[68:69], v[148:149], v[168:169] op_sel:[0,0,0] op_sel_hi:[1,0,1]
	v_pk_fma_f32 v[142:143], v[142:143], v[148:149], v[154:155] op_sel:[0,1,0] op_sel_hi:[1,1,1]
	v_pk_fma_f32 v[144:145], v[144:145], v[148:149], v[156:157] op_sel:[0,1,0] op_sel_hi:[1,1,1]
	v_pk_fma_f32 v[82:83], v[82:83], v[148:149], v[158:159] op_sel:[0,1,0] op_sel_hi:[1,1,1]
	v_pk_fma_f32 v[84:85], v[84:85], v[148:149], v[160:161] op_sel:[0,1,0] op_sel_hi:[1,1,1]
	v_pk_fma_f32 v[138:139], v[138:139], v[148:149], v[162:163] op_sel:[0,1,0] op_sel_hi:[1,1,1]
	v_pk_fma_f32 v[140:141], v[140:141], v[148:149], v[164:165] op_sel:[0,1,0] op_sel_hi:[1,1,1]
	v_pk_fma_f32 v[98:99], v[98:99], v[148:149], v[166:167] op_sel:[0,1,0] op_sel_hi:[1,1,1]
	v_pk_fma_f32 v[100:101], v[100:101], v[148:149], v[168:169] op_sel:[0,1,0] op_sel_hi:[1,1,1]
	v_pk_fma_f32 v[94:95], v[94:95], v[150:151], v[154:155] op_sel:[0,0,0] op_sel_hi:[1,0,1]
	v_pk_fma_f32 v[96:97], v[96:97], v[150:151], v[156:157] op_sel:[0,0,0] op_sel_hi:[1,0,1]
	v_pk_fma_f32 v[10:11], v[10:11], v[150:151], v[158:159] op_sel:[0,0,0] op_sel_hi:[1,0,1]
	v_pk_fma_f32 v[12:13], v[12:13], v[150:151], v[160:161] op_sel:[0,0,0] op_sel_hi:[1,0,1]
	v_pk_fma_f32 v[110:111], v[110:111], v[150:151], v[162:163] op_sel:[0,0,0] op_sel_hi:[1,0,1]
	v_pk_fma_f32 v[112:113], v[112:113], v[150:151], v[164:165] op_sel:[0,0,0] op_sel_hi:[1,0,1]
	v_pk_fma_f32 v[22:23], v[22:23], v[150:151], v[166:167] op_sel:[0,0,0] op_sel_hi:[1,0,1]
	v_pk_fma_f32 v[24:25], v[24:25], v[150:151], v[168:169] op_sel:[0,0,0] op_sel_hi:[1,0,1]
	v_pk_fma_f32 v[90:91], v[90:91], v[150:151], v[154:155] op_sel:[0,1,0] op_sel_hi:[1,1,1]
	v_pk_fma_f32 v[92:93], v[92:93], v[150:151], v[156:157] op_sel:[0,1,0] op_sel_hi:[1,1,1]
	v_pk_fma_f32 v[6:7], v[6:7], v[150:151], v[158:159] op_sel:[0,1,0] op_sel_hi:[1,1,1]
	v_pk_fma_f32 v[8:9], v[8:9], v[150:151], v[160:161] op_sel:[0,1,0] op_sel_hi:[1,1,1]
	v_pk_fma_f32 v[106:107], v[106:107], v[150:151], v[162:163] op_sel:[0,1,0] op_sel_hi:[1,1,1]
	v_pk_fma_f32 v[108:109], v[108:109], v[150:151], v[164:165] op_sel:[0,1,0] op_sel_hi:[1,1,1]
	v_pk_fma_f32 v[18:19], v[18:19], v[150:151], v[166:167] op_sel:[0,1,0] op_sel_hi:[1,1,1]
	v_pk_fma_f32 v[20:21], v[20:21], v[150:151], v[168:169] op_sel:[0,1,0] op_sel_hi:[1,1,1]
	v_pk_fma_f32 v[86:87], v[86:87], v[152:153], v[154:155] op_sel:[0,0,0] op_sel_hi:[1,0,1]
	v_pk_fma_f32 v[88:89], v[88:89], v[152:153], v[156:157] op_sel:[0,0,0] op_sel_hi:[1,0,1]
	v_pk_fma_f32 v[2:3], v[2:3], v[152:153], v[158:159] op_sel:[0,0,0] op_sel_hi:[1,0,1]
	v_pk_fma_f32 v[4:5], v[4:5], v[152:153], v[160:161] op_sel:[0,0,0] op_sel_hi:[1,0,1]
	v_pk_fma_f32 v[102:103], v[102:103], v[152:153], v[162:163] op_sel:[0,0,0] op_sel_hi:[1,0,1]
	v_pk_fma_f32 v[104:105], v[104:105], v[152:153], v[164:165] op_sel:[0,0,0] op_sel_hi:[1,0,1]
	v_pk_fma_f32 v[14:15], v[14:15], v[152:153], v[166:167] op_sel:[0,0,0] op_sel_hi:[1,0,1]
	v_pk_fma_f32 v[16:17], v[16:17], v[152:153], v[168:169] op_sel:[0,0,0] op_sel_hi:[1,0,1]
	v_pk_fma_f32 v[114:115], v[114:115], v[152:153], v[154:155] op_sel:[0,1,0] op_sel_hi:[1,1,1]
	v_pk_fma_f32 v[116:117], v[116:117], v[152:153], v[156:157] op_sel:[0,1,0] op_sel_hi:[1,1,1]
	v_pk_fma_f32 v[26:27], v[26:27], v[152:153], v[158:159] op_sel:[0,1,0] op_sel_hi:[1,1,1]
	v_pk_fma_f32 v[28:29], v[28:29], v[152:153], v[160:161] op_sel:[0,1,0] op_sel_hi:[1,1,1]
	v_pk_fma_f32 v[126:127], v[126:127], v[152:153], v[162:163] op_sel:[0,1,0] op_sel_hi:[1,1,1]
	v_pk_fma_f32 v[128:129], v[128:129], v[152:153], v[164:165] op_sel:[0,1,0] op_sel_hi:[1,1,1]
	v_pk_fma_f32 v[58:59], v[58:59], v[152:153], v[166:167] op_sel:[0,1,0] op_sel_hi:[1,1,1]
	v_pk_fma_f32 v[60:61], v[60:61], v[152:153], v[168:169] op_sel:[0,1,0] op_sel_hi:[1,1,1]
	v_cmp_eq_u32_e32 vcc, 15, v224
	s_and_saveexec_b64 s[8:9], vcc
	ds_write_b128 v227, v[46:49] offset:2048
	ds_write_b128 v227, v[34:37] offset:2064
	ds_write_b128 v227, v[78:81] offset:2560
	ds_write_b128 v227, v[66:69] offset:2576
	ds_write_b128 v227, v[142:145] offset:3072
	ds_write_b128 v227, v[82:85] offset:3088
	ds_write_b128 v227, v[138:141] offset:3584
	ds_write_b128 v227, v[98:101] offset:3600
	ds_write_b128 v227, v[86:89] offset:6144
	ds_write_b128 v227, v[2:5] offset:6160
	ds_write_b128 v227, v[102:105] offset:6656
	ds_write_b128 v227, v[14:17] offset:6672
	ds_write_b128 v227, v[114:117] offset:7168
	ds_write_b128 v227, v[26:29] offset:7184
	ds_write_b128 v227, v[126:129] offset:7680
	ds_write_b128 v227, v[58:61] offset:7696
	s_cmp_lg_u32 s54, 1
	s_cbranch_scc1 .Lnepib_nohalo
	s_add_u32 s52, s88, 0x2a00000
	s_addc_u32 s53, s89, 0
	global_store_dwordx4 v228, v[86:89], s[52:53] offset:0
	global_store_dwordx4 v228, v[2:5], s[52:53] offset:16
	global_store_dwordx4 v229, v[102:105], s[52:53] offset:0
	global_store_dwordx4 v229, v[14:17], s[52:53] offset:16
	global_store_dwordx4 v230, v[114:117], s[52:53] offset:0
	global_store_dwordx4 v230, v[26:29], s[52:53] offset:16
	global_store_dwordx4 v231, v[126:129], s[52:53] offset:0
	global_store_dwordx4 v231, v[58:61], s[52:53] offset:16
.Lnepib_nohalo:
	s_or_b64 exec, exec, s[8:9]
	s_cmp_lg_u32 s54, 0
	s_cbranch_scc1 .Lnepib_noalign
	s_barrier
.Lnepib_noalign:
	s_waitcnt lgkmcnt(0)
	s_barrier
	s_cmp_eq_u32 s54, 0
	s_cbranch_scc1 .Lnepib_z0
	ds_read_b128 v[118:121], v227 offset:512
	ds_read_b128 v[122:125], v227 offset:1536
	s_branch .Lnepib_j0
